# kind-2 GEMM residual epilogue (h += acc): tile groups transposed through the per-wave LDS buffer so h loads/stores are 8 rows x 128 B with adjacent lanes contiguous; loads 6 groups ahead
# speedup vs baseline: 1.0378x; 1.0134x over previous
.LBB0_480:
	s_and_b64 vcc, exec, s[12:13]
	s_cbranch_vccnz .Lres_orig
	v_lshrrev_b32_e32 v145, 6, v154
	v_bfe_u32 v146, v163, 5, 2
	v_lshl_add_u32 v145, v145, 2, v146
	v_mul_u32_u24_e32 v145, 2304, v145
	v_add_u32_e32 v145, 135424, v145
	v_and_b32_e32 v146, 15, v189
	v_mul_u32_u24_e32 v146, 144, v146
	v_lshrrev_b32_e32 v147, 4, v189
	v_lshl_add_u32 v146, v147, 5, v146
	v_add_u32_e32 v152, v145, v146
	v_lshrrev_b32_e32 v146, 3, v189
	v_and_b32_e32 v147, 7, v189
	v_mul_u32_u24_e32 v153, 144, v146
	v_lshl_add_u32 v153, v147, 4, v153
	v_add_u32_e32 v153, v145, v153
	v_and_b32_e32 v148, 0xfffffff0, v154
	v_add_u32_e32 v148, v148, v146
	v_lshl_add_u32 v148, s23, 8, v148
	v_and_b32_e32 v149, 0x60, v163
	v_lshl_add_u32 v149, s22, 8, v149
	v_lshlrev_b32_e32 v148, 12, v148
	v_lshl_add_u32 v149, v149, 2, v148
	v_lshl_add_u32 v144, v147, 4, v149
	v_mov_b32_e32 v145, v144
	v_add_u32_e32 v146, 0x8000, v144
	global_load_dwordx4 v[192:195], v145, s[72:73]
	global_load_dwordx4 v[196:199], v146, s[72:73]
	v_add_u32_e32 v147, 0x200, v144
	v_add_u32_e32 v148, 0x8200, v144
	global_load_dwordx4 v[200:203], v147, s[72:73]
	global_load_dwordx4 v[204:207], v148, s[72:73]
	v_add_u32_e32 v149, 0x10000, v144
	v_add_u32_e32 v150, 0x18000, v144
	global_load_dwordx4 v[208:211], v149, s[72:73]
	global_load_dwordx4 v[212:215], v150, s[72:73]
	v_add_u32_e32 v145, 0x10200, v144
	v_add_u32_e32 v146, 0x18200, v144
	global_load_dwordx4 v[216:219], v145, s[72:73]
	global_load_dwordx4 v[220:223], v146, s[72:73]
	v_add_u32_e32 v147, 0x20000, v144
	v_add_u32_e32 v148, 0x28000, v144
	global_load_dwordx4 v[224:227], v147, s[72:73]
	global_load_dwordx4 v[228:231], v148, s[72:73]
	v_add_u32_e32 v149, 0x20200, v144
	v_add_u32_e32 v150, 0x28200, v144
	global_load_dwordx4 v[232:235], v149, s[72:73]
	global_load_dwordx4 v[236:239], v150, s[72:73]
	ds_write_b128 v152, v[126:129]
	ds_write_b128 v152, v[122:125] offset:16
	ds_read_b128 v[240:243], v153
	ds_read_b128 v[244:247], v153 offset:1152
	ds_write_b128 v152, v[118:121]
	ds_write_b128 v152, v[114:117] offset:16
	ds_read_b128 v[130:133], v153
	ds_read_b128 v[176:179], v153 offset:1152
	s_waitcnt lgkmcnt(4)
	s_waitcnt vmcnt(10)
	v_pk_add_f32 v[240:241], v[240:241], v[192:193]
	v_pk_add_f32 v[242:243], v[242:243], v[194:195]
	v_pk_add_f32 v[244:245], v[244:245], v[196:197]
	v_pk_add_f32 v[246:247], v[246:247], v[198:199]
	v_mov_b32_e32 v180, v144
	v_add_u32_e32 v181, 0x8000, v144
	global_store_dwordx4 v180, v[240:243], s[72:73]
	global_store_dwordx4 v181, v[244:247], s[72:73]
	v_add_u32_e32 v145, 0x30000, v144
	v_add_u32_e32 v146, 0x38000, v144
	global_load_dwordx4 v[192:195], v145, s[72:73]
	global_load_dwordx4 v[196:199], v146, s[72:73]
	ds_write_b128 v152, v[108:111]
	ds_write_b128 v152, v[104:107] offset:16
	ds_read_b128 v[240:243], v153
	ds_read_b128 v[244:247], v153 offset:1152
	s_waitcnt lgkmcnt(4)
	s_waitcnt vmcnt(12)
	v_pk_add_f32 v[130:131], v[130:131], v[200:201]
	v_pk_add_f32 v[132:133], v[132:133], v[202:203]
	v_pk_add_f32 v[176:177], v[176:177], v[204:205]
	v_pk_add_f32 v[178:179], v[178:179], v[206:207]
	v_add_u32_e32 v180, 0x200, v144
	v_add_u32_e32 v181, 0x8200, v144
	global_store_dwordx4 v180, v[130:133], s[72:73]
	global_store_dwordx4 v181, v[176:179], s[72:73]
	v_add_u32_e32 v147, 0x30200, v144
	v_add_u32_e32 v148, 0x38200, v144
	global_load_dwordx4 v[200:203], v147, s[72:73]
	global_load_dwordx4 v[204:207], v148, s[72:73]
	ds_write_b128 v152, v[100:103]
	ds_write_b128 v152, v[96:99] offset:16
	ds_read_b128 v[130:133], v153
	ds_read_b128 v[176:179], v153 offset:1152
	s_waitcnt lgkmcnt(4)
	s_waitcnt vmcnt(14)
	v_pk_add_f32 v[240:241], v[240:241], v[208:209]
	v_pk_add_f32 v[242:243], v[242:243], v[210:211]
	v_pk_add_f32 v[244:245], v[244:245], v[212:213]
	v_pk_add_f32 v[246:247], v[246:247], v[214:215]
	v_add_u32_e32 v180, 0x10000, v144
	v_add_u32_e32 v181, 0x18000, v144
	global_store_dwordx4 v180, v[240:243], s[72:73]
	global_store_dwordx4 v181, v[244:247], s[72:73]
	v_add_u32_e32 v149, 0x80000, v144
	v_add_u32_e32 v150, 0x88000, v144
	global_load_dwordx4 v[208:211], v149, s[72:73]
	global_load_dwordx4 v[212:215], v150, s[72:73]
	ds_write_b128 v152, v[92:95]
	ds_write_b128 v152, v[88:91] offset:16
	ds_read_b128 v[240:243], v153
	ds_read_b128 v[244:247], v153 offset:1152
	s_waitcnt lgkmcnt(4)
	s_waitcnt vmcnt(16)
	v_pk_add_f32 v[130:131], v[130:131], v[216:217]
	v_pk_add_f32 v[132:133], v[132:133], v[218:219]
	v_pk_add_f32 v[176:177], v[176:177], v[220:221]
	v_pk_add_f32 v[178:179], v[178:179], v[222:223]
	v_add_u32_e32 v180, 0x10200, v144
	v_add_u32_e32 v181, 0x18200, v144
	global_store_dwordx4 v180, v[130:133], s[72:73]
	global_store_dwordx4 v181, v[176:179], s[72:73]
	v_add_u32_e32 v145, 0x80200, v144
	v_add_u32_e32 v146, 0x88200, v144
	global_load_dwordx4 v[216:219], v145, s[72:73]
	global_load_dwordx4 v[220:223], v146, s[72:73]
	ds_write_b128 v152, v[84:87]
	ds_write_b128 v152, v[80:83] offset:16
	ds_read_b128 v[130:133], v153
	ds_read_b128 v[176:179], v153 offset:1152
	s_waitcnt lgkmcnt(4)
	s_waitcnt vmcnt(18)
	v_pk_add_f32 v[240:241], v[240:241], v[224:225]
	v_pk_add_f32 v[242:243], v[242:243], v[226:227]
	v_pk_add_f32 v[244:245], v[244:245], v[228:229]
	v_pk_add_f32 v[246:247], v[246:247], v[230:231]
	v_add_u32_e32 v180, 0x20000, v144
	v_add_u32_e32 v181, 0x28000, v144
	global_store_dwordx4 v180, v[240:243], s[72:73]
	global_store_dwordx4 v181, v[244:247], s[72:73]
	v_add_u32_e32 v147, 0x90000, v144
	v_add_u32_e32 v148, 0x98000, v144
	global_load_dwordx4 v[224:227], v147, s[72:73]
	global_load_dwordx4 v[228:231], v148, s[72:73]
	ds_write_b128 v152, v[76:79]
	ds_write_b128 v152, v[72:75] offset:16
	ds_read_b128 v[240:243], v153
	ds_read_b128 v[244:247], v153 offset:1152
	s_waitcnt lgkmcnt(4)
	s_waitcnt vmcnt(20)
	v_pk_add_f32 v[130:131], v[130:131], v[232:233]
	v_pk_add_f32 v[132:133], v[132:133], v[234:235]
	v_pk_add_f32 v[176:177], v[176:177], v[236:237]
	v_pk_add_f32 v[178:179], v[178:179], v[238:239]
	v_add_u32_e32 v180, 0x20200, v144
	v_add_u32_e32 v181, 0x28200, v144
	global_store_dwordx4 v180, v[130:133], s[72:73]
	global_store_dwordx4 v181, v[176:179], s[72:73]
	v_add_u32_e32 v149, 0x90200, v144
	v_add_u32_e32 v150, 0x98200, v144
	global_load_dwordx4 v[232:235], v149, s[72:73]
	global_load_dwordx4 v[236:239], v150, s[72:73]
	ds_write_b128 v152, v[68:71]
	ds_write_b128 v152, v[64:67] offset:16
	ds_read_b128 v[130:133], v153
	ds_read_b128 v[176:179], v153 offset:1152
	s_waitcnt lgkmcnt(4)
	s_waitcnt vmcnt(20)
	v_pk_add_f32 v[240:241], v[240:241], v[192:193]
	v_pk_add_f32 v[242:243], v[242:243], v[194:195]
	v_pk_add_f32 v[244:245], v[244:245], v[196:197]
	v_pk_add_f32 v[246:247], v[246:247], v[198:199]
	v_add_u32_e32 v180, 0x30000, v144
	v_add_u32_e32 v181, 0x38000, v144
	global_store_dwordx4 v180, v[240:243], s[72:73]
	global_store_dwordx4 v181, v[244:247], s[72:73]
	v_add_u32_e32 v145, 0xa0000, v144
	v_add_u32_e32 v146, 0xa8000, v144
	global_load_dwordx4 v[192:195], v145, s[72:73]
	global_load_dwordx4 v[196:199], v146, s[72:73]
	ds_write_b128 v152, v[60:63]
	ds_write_b128 v152, v[56:59] offset:16
	ds_read_b128 v[240:243], v153
	ds_read_b128 v[244:247], v153 offset:1152
	s_waitcnt lgkmcnt(4)
	s_waitcnt vmcnt(20)
	v_pk_add_f32 v[130:131], v[130:131], v[200:201]
	v_pk_add_f32 v[132:133], v[132:133], v[202:203]
	v_pk_add_f32 v[176:177], v[176:177], v[204:205]
	v_pk_add_f32 v[178:179], v[178:179], v[206:207]
	v_add_u32_e32 v180, 0x30200, v144
	v_add_u32_e32 v181, 0x38200, v144
	global_store_dwordx4 v180, v[130:133], s[72:73]
	global_store_dwordx4 v181, v[176:179], s[72:73]
	v_add_u32_e32 v147, 0xa0200, v144
	v_add_u32_e32 v148, 0xa8200, v144
	global_load_dwordx4 v[200:203], v147, s[72:73]
	global_load_dwordx4 v[204:207], v148, s[72:73]
	ds_write_b128 v152, v[52:55]
	ds_write_b128 v152, v[48:51] offset:16
	ds_read_b128 v[130:133], v153
	ds_read_b128 v[176:179], v153 offset:1152
	s_waitcnt lgkmcnt(4)
	s_waitcnt vmcnt(20)
	v_pk_add_f32 v[240:241], v[240:241], v[208:209]
	v_pk_add_f32 v[242:243], v[242:243], v[210:211]
	v_pk_add_f32 v[244:245], v[244:245], v[212:213]
	v_pk_add_f32 v[246:247], v[246:247], v[214:215]
	v_add_u32_e32 v180, 0x80000, v144
	v_add_u32_e32 v181, 0x88000, v144
	global_store_dwordx4 v180, v[240:243], s[72:73]
	global_store_dwordx4 v181, v[244:247], s[72:73]
	v_add_u32_e32 v149, 0xb0000, v144
	v_add_u32_e32 v150, 0xb8000, v144
	global_load_dwordx4 v[208:211], v149, s[72:73]
	global_load_dwordx4 v[212:215], v150, s[72:73]
	ds_write_b128 v152, v[44:47]
	ds_write_b128 v152, v[40:43] offset:16
	ds_read_b128 v[240:243], v153
	ds_read_b128 v[244:247], v153 offset:1152
	s_waitcnt lgkmcnt(4)
	s_waitcnt vmcnt(20)
	v_pk_add_f32 v[130:131], v[130:131], v[216:217]
	v_pk_add_f32 v[132:133], v[132:133], v[218:219]
	v_pk_add_f32 v[176:177], v[176:177], v[220:221]
	v_pk_add_f32 v[178:179], v[178:179], v[222:223]
	v_add_u32_e32 v180, 0x80200, v144
	v_add_u32_e32 v181, 0x88200, v144
	global_store_dwordx4 v180, v[130:133], s[72:73]
	global_store_dwordx4 v181, v[176:179], s[72:73]
	v_add_u32_e32 v145, 0xb0200, v144
	v_add_u32_e32 v146, 0xb8200, v144
	global_load_dwordx4 v[216:219], v145, s[72:73]
	global_load_dwordx4 v[220:223], v146, s[72:73]
	ds_write_b128 v152, v[36:39]
	ds_write_b128 v152, v[32:35] offset:16
	ds_read_b128 v[130:133], v153
	ds_read_b128 v[176:179], v153 offset:1152
	s_waitcnt lgkmcnt(4)
	s_waitcnt vmcnt(20)
	v_pk_add_f32 v[240:241], v[240:241], v[224:225]
	v_pk_add_f32 v[242:243], v[242:243], v[226:227]
	v_pk_add_f32 v[244:245], v[244:245], v[228:229]
	v_pk_add_f32 v[246:247], v[246:247], v[230:231]
	v_add_u32_e32 v180, 0x90000, v144
	v_add_u32_e32 v181, 0x98000, v144
	global_store_dwordx4 v180, v[240:243], s[72:73]
	global_store_dwordx4 v181, v[244:247], s[72:73]
	ds_write_b128 v152, v[28:31]
	ds_write_b128 v152, v[24:27] offset:16
	ds_read_b128 v[240:243], v153
	ds_read_b128 v[244:247], v153 offset:1152
	s_waitcnt lgkmcnt(4)
	s_waitcnt vmcnt(18)
	v_pk_add_f32 v[130:131], v[130:131], v[232:233]
	v_pk_add_f32 v[132:133], v[132:133], v[234:235]
	v_pk_add_f32 v[176:177], v[176:177], v[236:237]
	v_pk_add_f32 v[178:179], v[178:179], v[238:239]
	v_add_u32_e32 v180, 0x90200, v144
	v_add_u32_e32 v181, 0x98200, v144
	global_store_dwordx4 v180, v[130:133], s[72:73]
	global_store_dwordx4 v181, v[176:179], s[72:73]
	ds_write_b128 v152, v[20:23]
	ds_write_b128 v152, v[16:19] offset:16
	ds_read_b128 v[130:133], v153
	ds_read_b128 v[176:179], v153 offset:1152
	s_waitcnt lgkmcnt(4)
	s_waitcnt vmcnt(16)
	v_pk_add_f32 v[240:241], v[240:241], v[192:193]
	v_pk_add_f32 v[242:243], v[242:243], v[194:195]
	v_pk_add_f32 v[244:245], v[244:245], v[196:197]
	v_pk_add_f32 v[246:247], v[246:247], v[198:199]
	v_add_u32_e32 v180, 0xa0000, v144
	v_add_u32_e32 v181, 0xa8000, v144
	global_store_dwordx4 v180, v[240:243], s[72:73]
	global_store_dwordx4 v181, v[244:247], s[72:73]
	ds_write_b128 v152, v[12:15]
	ds_write_b128 v152, v[8:11] offset:16
	ds_read_b128 v[240:243], v153
	ds_read_b128 v[244:247], v153 offset:1152
	s_waitcnt lgkmcnt(4)
	s_waitcnt vmcnt(14)
	v_pk_add_f32 v[130:131], v[130:131], v[200:201]
	v_pk_add_f32 v[132:133], v[132:133], v[202:203]
	v_pk_add_f32 v[176:177], v[176:177], v[204:205]
	v_pk_add_f32 v[178:179], v[178:179], v[206:207]
	v_add_u32_e32 v180, 0xa0200, v144
	v_add_u32_e32 v181, 0xa8200, v144
	global_store_dwordx4 v180, v[130:133], s[72:73]
	global_store_dwordx4 v181, v[176:179], s[72:73]
	ds_write_b128 v152, v[4:7]
	ds_write_b128 v152, v[0:3] offset:16
	ds_read_b128 v[130:133], v153
	ds_read_b128 v[176:179], v153 offset:1152
	s_waitcnt lgkmcnt(4)
	s_waitcnt vmcnt(12)
	v_pk_add_f32 v[240:241], v[240:241], v[208:209]
	v_pk_add_f32 v[242:243], v[242:243], v[210:211]
	v_pk_add_f32 v[244:245], v[244:245], v[212:213]
	v_pk_add_f32 v[246:247], v[246:247], v[214:215]
	v_add_u32_e32 v180, 0xb0000, v144
	v_add_u32_e32 v181, 0xb8000, v144
	global_store_dwordx4 v180, v[240:243], s[72:73]
	global_store_dwordx4 v181, v[244:247], s[72:73]
	s_waitcnt lgkmcnt(0)
	s_waitcnt vmcnt(10)
	v_pk_add_f32 v[130:131], v[130:131], v[216:217]
	v_pk_add_f32 v[132:133], v[132:133], v[218:219]
	v_pk_add_f32 v[176:177], v[176:177], v[220:221]
	v_pk_add_f32 v[178:179], v[178:179], v[222:223]
	v_add_u32_e32 v180, 0xb0200, v144
	v_add_u32_e32 v181, 0xb8200, v144
	global_store_dwordx4 v180, v[130:133], s[72:73]
	global_store_dwordx4 v181, v[176:179], s[72:73]
	s_branch .Lres_join
